# GU GEMM: wave groups stay staggered across the tile epilogue (align barrier only after the last unit), on top of the LRU parameter-load hoist
# baseline (speedup 1.0000x reference)
; #define PG8_STAGE(bufoff, gbase, voff) do { _Pragma("unroll") for (int _i = 0; _i < 2; ++_i) \
;         __builtin_amdgcn_global_load_lds((const unsigned*)((const char*)(gbase) + (voff)[_i]), (LAS unsigned*)(lds + (bufoff) + ldsw + _i * 8192), 16, 0, 0); } while (0)
; #define PG8_LDA(dst, b, h) do { _Pragma("unroll") for (int m = 0; m < 4; ++m) _Pragma("unroll") for (int k = 0; k < 2; ++k) dst[m][k] = *(const LAS bf16x8*)(lds + PG8_SA(b, h) + aoff + m * 2048 + k * 1024); } while (0)
; #define PG8_LDB(dst, b, h) do { _Pragma("unroll") for (int n = 0; n < 2; ++n) _Pragma("unroll") for (int k = 0; k < 2; ++k) dst[n][k] = *(const LAS bf16x8*)(lds + PG8_SB(b, h) + boff + n * 2048 + k * 1024); } while (0)
; #define PG8_MMA(ai, bj, At, Bt) do { __builtin_amdgcn_s_setprio(1); _Pragma("unroll") for (int m = 0; m < 4; ++m) _Pragma("unroll") for (int n = 0; n < 2; ++n) _Pragma("unroll") for (int k = 0; k < 2; ++k) \
;         acc[ai][bj][m][n] = __builtin_amdgcn_mfma_f32_16x16x32_bf16(Bt[n][k], At[m][k], acc[ai][bj][m][n], 0, 0, 0); __builtin_amdgcn_s_setprio(0); } while (0)
; #define PG8_WAIT_V(n) asm volatile("s_waitcnt vmcnt(" #n ")" ::: "memory")
; #define PG8_WAIT_L(n) asm volatile("s_waitcnt lgkmcnt(" #n ")" ::: "memory")
; #define PG8_BAR __builtin_amdgcn_s_barrier()
; #define PG8_SCHED __builtin_amdgcn_sched_barrier(0)
; template <class Epi, class Sched>
; __device__ __forceinline__ void gemm_phase(LAS unsigned char* lds, const int K, const Sched& S, const Epi& E) {
;     ...
;             PG8_LDB(B0, 0, 0); PG8_LDB(B1, 0, 1); PG8_SCHED; PG8_LDA(At, 0, 0); PG8_STAGE(PG8_SA(1, 1), a1 + hstep, voffA);
;             PG8_WAIT_V(8); PG8_WAIT_L(0); PG8_BAR; PG8_MMA(0, 0, At, B0); PG8_MMA(0, 1, At, B1); PG8_BAR; PG8_SCHED;
;             PG8_LDA(At, 0, 1); PG8_STAGE(PG8_SB(0, 0), b2, voffB); PG8_STAGE(PG8_SB(0, 1), b2 + hstep, voffB); PG8_STAGE(PG8_SA(0, 0), a2, voffA);
;             PG8_WAIT_V(8); PG8_WAIT_L(0); PG8_BAR; PG8_MMA(1, 0, At, B0); PG8_MMA(1, 1, At, B1); PG8_BAR; PG8_SCHED;
.LBB0_963:
	s_add_u32 s5, s56, 0xfffc0080
	s_addc_u32 s9, s57, -1
	s_add_i32 s10, 0, 0x10000
	s_cmp_eq_u32 s4, 12
	s_cselect_b32 s61, s53, s9
	s_cselect_b32 s60, s52, s5
	v_add_u32_e32 v150, s10, v153
	s_cselect_b32 s59, s55, s2
	s_cselect_b32 s58, s54, s1
	s_add_i32 s5, 0, 0x14000
	ds_read_b128 v[156:159], v150
	ds_read_b128 v[160:163], v150 offset:1024
	ds_read_b128 v[164:167], v150 offset:2048
	ds_read_b128 v[180:183], v150 offset:3072
	v_add_u32_e32 v150, s5, v153
	ds_read_b128 v[184:187], v150
	ds_read_b128 v[188:191], v150 offset:1024
	ds_read_b128 v[192:195], v150 offset:2048
	ds_read_b128 v[196:199], v150 offset:3072
	v_lshl_add_u64 v[150:151], s[56:57], 0, v[146:147]
	s_add_i32 m0, s66, 0xc000
	ds_read_b128 v[200:203], v154
	ds_read_b128 v[204:207], v154 offset:1024
	ds_read_b128 v[208:211], v154 offset:2048
	ds_read_b128 v[212:215], v154 offset:3072
	ds_read_b128 v[216:219], v154 offset:4096
	ds_read_b128 v[220:223], v154 offset:5120
	ds_read_b128 v[224:227], v154 offset:6144
	ds_read_b128 v[228:231], v154 offset:7168
	global_load_lds_dwordx4 v[150:151], off
	v_lshl_add_u64 v[150:151], s[56:57], 0, v[148:149]
	s_add_i32 m0, s66, 0xe000
	s_nop 0
	global_load_lds_dwordx4 v[150:151], off
	s_waitcnt vmcnt(8)
	s_waitcnt lgkmcnt(0)
	s_barrier
	s_setprio 1
	s_waitcnt lgkmcnt(0)
	v_mfma_f32_16x16x32_bf16 v[124:127], v[156:159], v[200:203], v[124:127]
	v_mfma_f32_16x16x32_bf16 v[116:119], v[164:167], v[200:203], v[116:119]
	v_mfma_f32_16x16x32_bf16 v[108:111], v[156:159], v[208:211], v[108:111]
	v_mfma_f32_16x16x32_bf16 v[100:103], v[164:167], v[208:211], v[100:103]
	v_mfma_f32_16x16x32_bf16 v[92:95], v[156:159], v[216:219], v[92:95]
	v_mfma_f32_16x16x32_bf16 v[84:87], v[164:167], v[216:219], v[84:87]
	v_mfma_f32_16x16x32_bf16 v[76:79], v[156:159], v[224:227], v[76:79]
	v_mfma_f32_16x16x32_bf16 v[68:71], v[164:167], v[224:227], v[68:71]
	v_mfma_f32_16x16x32_bf16 v[124:127], v[160:163], v[204:207], v[124:127]
	v_mfma_f32_16x16x32_bf16 v[116:119], v[180:183], v[204:207], v[116:119]
	v_mfma_f32_16x16x32_bf16 v[108:111], v[160:163], v[212:215], v[108:111]
	v_mfma_f32_16x16x32_bf16 v[100:103], v[180:183], v[212:215], v[100:103]
	v_mfma_f32_16x16x32_bf16 v[92:95], v[160:163], v[220:223], v[92:95]
	v_mfma_f32_16x16x32_bf16 v[84:87], v[180:183], v[220:223], v[84:87]
	v_mfma_f32_16x16x32_bf16 v[76:79], v[160:163], v[228:231], v[76:79]
	v_mfma_f32_16x16x32_bf16 v[68:71], v[180:183], v[228:231], v[68:71]
	s_setprio 0
	s_setprio 1
	v_mfma_f32_16x16x32_bf16 v[120:123], v[184:187], v[200:203], v[120:123]
	v_mfma_f32_16x16x32_bf16 v[112:115], v[192:195], v[200:203], v[112:115]
	v_mfma_f32_16x16x32_bf16 v[104:107], v[184:187], v[208:211], v[104:107]
	v_mfma_f32_16x16x32_bf16 v[96:99], v[192:195], v[208:211], v[96:99]
	v_mfma_f32_16x16x32_bf16 v[88:91], v[184:187], v[216:219], v[88:91]
	v_mfma_f32_16x16x32_bf16 v[80:83], v[192:195], v[216:219], v[80:83]
	v_mfma_f32_16x16x32_bf16 v[72:75], v[184:187], v[224:227], v[72:75]
	v_mfma_f32_16x16x32_bf16 v[64:67], v[192:195], v[224:227], v[64:67]
	v_mfma_f32_16x16x32_bf16 v[120:123], v[188:191], v[204:207], v[120:123]
	v_mfma_f32_16x16x32_bf16 v[112:115], v[196:199], v[204:207], v[112:115]
	v_mfma_f32_16x16x32_bf16 v[104:107], v[188:191], v[212:215], v[104:107]
	v_mfma_f32_16x16x32_bf16 v[96:99], v[196:199], v[212:215], v[96:99]
	v_mfma_f32_16x16x32_bf16 v[88:91], v[188:191], v[220:223], v[88:91]
	v_mfma_f32_16x16x32_bf16 v[80:83], v[196:199], v[220:223], v[80:83]
	v_mfma_f32_16x16x32_bf16 v[72:75], v[188:191], v[228:231], v[72:75]
	v_mfma_f32_16x16x32_bf16 v[64:67], v[196:199], v[228:231], v[64:67]
	s_setprio 0
	s_barrier
	s_add_i32 s9, s10, s63
	v_lshl_add_u64 v[150:151], s[58:59], 0, v[142:143]
	s_mov_b32 m0, s9
	ds_read_b128 v[200:203], v154 offset:16384
	ds_read_b128 v[204:207], v154 offset:17408
	ds_read_b128 v[208:211], v154 offset:18432
	ds_read_b128 v[212:215], v154 offset:19456
	ds_read_b128 v[216:219], v154 offset:20480
	ds_read_b128 v[220:223], v154 offset:21504
	ds_read_b128 v[224:227], v154 offset:22528
	ds_read_b128 v[228:231], v154 offset:23552
	global_load_lds_dwordx4 v[150:151], off
	s_add_i32 m0, s9, 0x2000
	s_add_u32 s10, s58, 0x40000
	v_lshl_add_u64 v[232:233], s[58:59], 0, v[138:139]
	s_addc_u32 s11, s59, 0
	s_add_i32 s5, s5, s63
	global_load_lds_dwordx4 v[232:233], off
	v_lshl_add_u64 v[234:235], s[10:11], 0, v[142:143]
	s_mov_b32 m0, s5
	v_lshl_add_u64 v[236:237], s[60:61], 0, v[140:141]
	global_load_lds_dwordx4 v[234:235], off
	v_lshl_add_u64 v[234:235], s[10:11], 0, v[138:139]
	s_add_i32 m0, s5, 0x2000
	s_nop 0
	global_load_lds_dwordx4 v[234:235], off
	v_lshl_add_u64 v[234:235], s[60:61], 0, v[144:145]
	s_mov_b32 m0, s66
	s_nop 0
	global_load_lds_dwordx4 v[234:235], off
	s_mov_b32 m0, s67
	s_nop 0
	global_load_lds_dwordx4 v[236:237], off
	s_waitcnt vmcnt(8)
	s_waitcnt lgkmcnt(0)
	s_barrier
; #define PG8_STAGE(bufoff, gbase, voff) do { _Pragma("unroll") for (int _i = 0; _i < 2; ++_i) \
;         __builtin_amdgcn_global_load_lds((const unsigned*)((const char*)(gbase) + (voff)[_i]), (LAS unsigned*)(lds + (bufoff) + ldsw + _i * 8192), 16, 0, 0); } while (0)
; #define PG8_LDA(dst, b, h) do { _Pragma("unroll") for (int m = 0; m < 4; ++m) _Pragma("unroll") for (int k = 0; k < 2; ++k) dst[m][k] = *(const LAS bf16x8*)(lds + PG8_SA(b, h) + aoff + m * 2048 + k * 1024); } while (0)
; #define PG8_LDB(dst, b, h) do { _Pragma("unroll") for (int n = 0; n < 2; ++n) _Pragma("unroll") for (int k = 0; k < 2; ++k) dst[n][k] = *(const LAS bf16x8*)(lds + PG8_SB(b, h) + boff + n * 2048 + k * 1024); } while (0)
; #define PG8_MMA(ai, bj, At, Bt) do { __builtin_amdgcn_s_setprio(1); _Pragma("unroll") for (int m = 0; m < 4; ++m) _Pragma("unroll") for (int n = 0; n < 2; ++n) _Pragma("unroll") for (int k = 0; k < 2; ++k) \
;         acc[ai][bj][m][n] = __builtin_amdgcn_mfma_f32_16x16x32_bf16(Bt[n][k], At[m][k], acc[ai][bj][m][n], 0, 0, 0); __builtin_amdgcn_s_setprio(0); } while (0)
; #define PG8_WAIT_V(n) asm volatile("s_waitcnt vmcnt(" #n ")" ::: "memory")
; #define PG8_WAIT_L(n) asm volatile("s_waitcnt lgkmcnt(" #n ")" ::: "memory")
; #define PG8_BAR __builtin_amdgcn_s_barrier()
; #define PG8_SCHED __builtin_amdgcn_sched_barrier(0)
; template <class Epi, class Sched>
; __device__ __forceinline__ void gemm_phase(LAS unsigned char* lds, const int K, const Sched& S, const Epi& E) {
;     ...
;             PG8_WAIT_V(8); PG8_WAIT_L(0); PG8_BAR; PG8_MMA(1, 0, At, B0); PG8_MMA(1, 1, At, B1); PG8_BAR; PG8_SCHED;
;             PG8_LDB(B0, 1, 0); PG8_LDB(B1, 1, 1); PG8_SCHED; PG8_LDA(At, 1, 0); PG8_STAGE(PG8_SA(0, 1), a2 + hstep, voffA);
;             PG8_WAIT_V(8); PG8_WAIT_L(0); PG8_BAR; PG8_MMA(0, 0, At, B0); PG8_MMA(0, 1, At, B1); PG8_BAR; PG8_SCHED;
	s_setprio 1
	s_waitcnt lgkmcnt(0)
	v_mfma_f32_16x16x32_bf16 v[60:63], v[156:159], v[200:203], v[60:63]
	v_mfma_f32_16x16x32_bf16 v[52:55], v[164:167], v[200:203], v[52:55]
	v_mfma_f32_16x16x32_bf16 v[44:47], v[156:159], v[208:211], v[44:47]
	v_mfma_f32_16x16x32_bf16 v[36:39], v[164:167], v[208:211], v[36:39]
	v_mfma_f32_16x16x32_bf16 v[28:31], v[156:159], v[216:219], v[28:31]
	v_mfma_f32_16x16x32_bf16 v[20:23], v[164:167], v[216:219], v[20:23]
	v_mfma_f32_16x16x32_bf16 v[12:15], v[156:159], v[224:227], v[12:15]
	v_mfma_f32_16x16x32_bf16 v[4:7], v[164:167], v[224:227], v[4:7]
	v_mfma_f32_16x16x32_bf16 v[60:63], v[160:163], v[204:207], v[60:63]
	v_mfma_f32_16x16x32_bf16 v[52:55], v[180:183], v[204:207], v[52:55]
	v_mfma_f32_16x16x32_bf16 v[44:47], v[160:163], v[212:215], v[44:47]
	v_mfma_f32_16x16x32_bf16 v[36:39], v[180:183], v[212:215], v[36:39]
	v_mfma_f32_16x16x32_bf16 v[28:31], v[160:163], v[220:223], v[28:31]
	v_mfma_f32_16x16x32_bf16 v[20:23], v[180:183], v[220:223], v[20:23]
	v_mfma_f32_16x16x32_bf16 v[12:15], v[160:163], v[228:231], v[12:15]
	v_mfma_f32_16x16x32_bf16 v[4:7], v[180:183], v[228:231], v[4:7]
	s_setprio 0
	s_setprio 1
	v_mfma_f32_16x16x32_bf16 v[56:59], v[184:187], v[200:203], v[56:59]
	v_mfma_f32_16x16x32_bf16 v[48:51], v[192:195], v[200:203], v[48:51]
	v_mfma_f32_16x16x32_bf16 v[40:43], v[184:187], v[208:211], v[40:43]
	v_mfma_f32_16x16x32_bf16 v[32:35], v[192:195], v[208:211], v[32:35]
	v_mfma_f32_16x16x32_bf16 v[24:27], v[184:187], v[216:219], v[24:27]
	v_mfma_f32_16x16x32_bf16 v[16:19], v[192:195], v[216:219], v[16:19]
	v_mfma_f32_16x16x32_bf16 v[8:11], v[184:187], v[224:227], v[8:11]
	v_mfma_f32_16x16x32_bf16 v[0:3], v[192:195], v[224:227], v[0:3]
	v_mfma_f32_16x16x32_bf16 v[56:59], v[188:191], v[204:207], v[56:59]
	v_mfma_f32_16x16x32_bf16 v[48:51], v[196:199], v[204:207], v[48:51]
	v_mfma_f32_16x16x32_bf16 v[40:43], v[188:191], v[212:215], v[40:43]
	v_mfma_f32_16x16x32_bf16 v[32:35], v[196:199], v[212:215], v[32:35]
	v_mfma_f32_16x16x32_bf16 v[24:27], v[188:191], v[220:223], v[24:27]
	v_mfma_f32_16x16x32_bf16 v[16:19], v[196:199], v[220:223], v[16:19]
	v_mfma_f32_16x16x32_bf16 v[8:11], v[188:191], v[228:231], v[8:11]
	v_mfma_f32_16x16x32_bf16 v[0:3], v[196:199], v[228:231], v[0:3]
	s_setprio 0
	s_barrier
	s_add_i32 s5, 0, 0x18000
	v_add_u32_e32 v155, s5, v153
	s_add_i32 s9, 0, 0x1c000
	ds_read_b128 v[156:159], v155
	ds_read_b128 v[160:163], v155 offset:1024
	ds_read_b128 v[164:167], v155 offset:2048
	ds_read_b128 v[180:183], v155 offset:3072
	v_add_u32_e32 v155, s9, v153
	ds_read_b128 v[184:187], v155
	ds_read_b128 v[188:191], v155 offset:1024
	ds_read_b128 v[192:195], v155 offset:2048
	ds_read_b128 v[196:199], v155 offset:3072
	s_add_u32 s10, s60, 0x40000
	s_addc_u32 s11, s61, 0
	s_mov_b32 m0, s68
	v_lshl_add_u64 v[238:239], s[10:11], 0, v[144:145]
	ds_read_b128 v[200:203], v154 offset:32768
	ds_read_b128 v[204:207], v154 offset:33792
	ds_read_b128 v[208:211], v154 offset:34816
	ds_read_b128 v[212:215], v154 offset:35840
	ds_read_b128 v[216:219], v154 offset:36864
	ds_read_b128 v[220:223], v154 offset:37888
	ds_read_b128 v[224:227], v154 offset:38912
	ds_read_b128 v[228:231], v154 offset:39936
	global_load_lds_dwordx4 v[238:239], off
	v_lshl_add_u64 v[238:239], s[10:11], 0, v[140:141]
	s_mov_b32 m0, s69
	s_nop 0
	global_load_lds_dwordx4 v[238:239], off
	s_waitcnt vmcnt(8)
	s_waitcnt lgkmcnt(0)
	s_barrier
	s_setprio 1
	s_waitcnt lgkmcnt(0)
	v_mfma_f32_16x16x32_bf16 v[124:127], v[156:159], v[200:203], v[124:127]
	v_mfma_f32_16x16x32_bf16 v[116:119], v[164:167], v[200:203], v[116:119]
	v_mfma_f32_16x16x32_bf16 v[108:111], v[156:159], v[208:211], v[108:111]
	v_mfma_f32_16x16x32_bf16 v[100:103], v[164:167], v[208:211], v[100:103]
	v_mfma_f32_16x16x32_bf16 v[92:95], v[156:159], v[216:219], v[92:95]
	v_mfma_f32_16x16x32_bf16 v[84:87], v[164:167], v[216:219], v[84:87]
	v_mfma_f32_16x16x32_bf16 v[76:79], v[156:159], v[224:227], v[76:79]
	v_mfma_f32_16x16x32_bf16 v[68:71], v[164:167], v[224:227], v[68:71]
	v_mfma_f32_16x16x32_bf16 v[124:127], v[160:163], v[204:207], v[124:127]
	v_mfma_f32_16x16x32_bf16 v[116:119], v[180:183], v[204:207], v[116:119]
	v_mfma_f32_16x16x32_bf16 v[108:111], v[160:163], v[212:215], v[108:111]
	v_mfma_f32_16x16x32_bf16 v[100:103], v[180:183], v[212:215], v[100:103]
	v_mfma_f32_16x16x32_bf16 v[92:95], v[160:163], v[220:223], v[92:95]
	v_mfma_f32_16x16x32_bf16 v[84:87], v[180:183], v[220:223], v[84:87]
	v_mfma_f32_16x16x32_bf16 v[76:79], v[160:163], v[228:231], v[76:79]
	v_mfma_f32_16x16x32_bf16 v[68:71], v[180:183], v[228:231], v[68:71]
	s_setprio 0
	s_setprio 1
	v_mfma_f32_16x16x32_bf16 v[120:123], v[184:187], v[200:203], v[120:123]
	v_mfma_f32_16x16x32_bf16 v[112:115], v[192:195], v[200:203], v[112:115]
	v_mfma_f32_16x16x32_bf16 v[104:107], v[184:187], v[208:211], v[104:107]
	v_mfma_f32_16x16x32_bf16 v[96:99], v[192:195], v[208:211], v[96:99]
	v_mfma_f32_16x16x32_bf16 v[88:91], v[184:187], v[216:219], v[88:91]
	v_mfma_f32_16x16x32_bf16 v[80:83], v[192:195], v[216:219], v[80:83]
	v_mfma_f32_16x16x32_bf16 v[72:75], v[184:187], v[224:227], v[72:75]
	v_mfma_f32_16x16x32_bf16 v[64:67], v[192:195], v[224:227], v[64:67]
	v_mfma_f32_16x16x32_bf16 v[120:123], v[188:191], v[204:207], v[120:123]
	v_mfma_f32_16x16x32_bf16 v[112:115], v[196:199], v[204:207], v[112:115]
	v_mfma_f32_16x16x32_bf16 v[104:107], v[188:191], v[212:215], v[104:107]
	v_mfma_f32_16x16x32_bf16 v[96:99], v[196:199], v[212:215], v[96:99]
	v_mfma_f32_16x16x32_bf16 v[88:91], v[188:191], v[220:223], v[88:91]
	v_mfma_f32_16x16x32_bf16 v[80:83], v[196:199], v[220:223], v[80:83]
	v_mfma_f32_16x16x32_bf16 v[72:75], v[188:191], v[228:231], v[72:75]
	v_mfma_f32_16x16x32_bf16 v[64:67], v[196:199], v[228:231], v[64:67]
	s_setprio 0
	s_barrier
; #define GAS __attribute__((address_space(1)))
; __device__ __forceinline__ unsigned cvt_pk_bf16(float lo, float hi) { unsigned r; asm volatile("v_cvt_pk_bf16_f32 %0, %1, %2" : "=v"(r) : "v"(lo), "v"(hi)); return r; }
; #define PG8_LDA(dst, b, h) do { _Pragma("unroll") for (int m = 0; m < 4; ++m) _Pragma("unroll") for (int k = 0; k < 2; ++k) dst[m][k] = *(const LAS bf16x8*)(lds + PG8_SA(b, h) + aoff + m * 2048 + k * 1024); } while (0)
;     __device__ __forceinline__ void operator()(const f32x4 (&acc)[2][2][4][2], const Unit& u, int wr, int wc, int fr, int fq) const {
;     ...
;             for (int m = 0; m < 4; ++m) { GAS bf16_t* rowp = p0 + (size_t)(ai * HALF + m * 16) * DFF;
;                 const f32x4 g0 = acc[ai][0][m][0], g1 = acc[ai][0][m][1], u0 = acc[ai][1][m][0], u1 = acc[ai][1][m][1]; f32x4 v0, v1;
; #pragma unroll
;                 for (int hj = 0; hj < 2; ++hj) {
;                     const f32x2 ga = (f32x2){g0[2 * hj], g0[2 * hj + 1]}, gb = (f32x2){g1[2 * hj], g1[2 * hj + 1]}, ua = (f32x2){u0[2 * hj], u0[2 * hj + 1]}, ub = (f32x2){u1[2 * hj], u1[2 * hj + 1]};
;                     const f32x2 ta = ga * (-1.4426950408889634f), tb = gb * (-1.4426950408889634f);
;                     const f32x2 da = (f32x2){__builtin_amdgcn_exp2f(ta.x), __builtin_amdgcn_exp2f(ta.y)} + 1.0f, db = (f32x2){__builtin_amdgcn_exp2f(tb.x), __builtin_amdgcn_exp2f(tb.y)} + 1.0f;
;                     const f32x2 ra = (ga * ua) * (f32x2){__builtin_amdgcn_rcpf(da.x), __builtin_amdgcn_rcpf(da.y)}, rb = (gb * ub) * (f32x2){__builtin_amdgcn_rcpf(db.x), __builtin_amdgcn_rcpf(db.y)};
;                     v0[2 * hj] = ra.x; v0[2 * hj + 1] = ra.y; v1[2 * hj] = rb.x; v1[2 * hj + 1] = rb.y; }
;                 u32x4 w; w.x = cvt_pk_bf16(v0[0], v0[1]); w.y = cvt_pk_bf16(v0[2], v0[3]); w.z = cvt_pk_bf16(v1[0], v1[1]); w.w = cvt_pk_bf16(v1[2], v1[3]);
;                 *(GAS u32x4*)rowp = w; }
; template <class Epi, class Sched>
; __device__ __forceinline__ void gemm_phase(LAS unsigned char* lds, const int K, const Sched& S, const Epi& E) {
;     ...
;             PG8_LDA(At, 1, 1); PG8_STAGE(PG8_SB(1, 0), b3, voffB); PG8_STAGE(PG8_SB(1, 1), b3 + hstep, voffB); PG8_STAGE(PG8_SA(1, 0), a3, voffA);
;             PG8_WAIT_V(8); PG8_WAIT_L(0); PG8_BAR; PG8_MMA(1, 0, At, B0); PG8_MMA(1, 1, At, B1); PG8_BAR; PG8_SCHED;
;         }
;         if (wr == 0) PG8_BAR;
;         E(acc, cur, wr, wc, fr, fq);
	s_add_i32 s5, s5, s63
	v_lshl_add_u64 v[150:151], v[150:151], 0, s[36:37]
	s_mov_b32 m0, s5
	ds_read_b128 v[200:203], v154 offset:49152
	ds_read_b128 v[204:207], v154 offset:50176
	ds_read_b128 v[208:211], v154 offset:51200
	ds_read_b128 v[212:215], v154 offset:52224
	ds_read_b128 v[216:219], v154 offset:53248
	ds_read_b128 v[220:223], v154 offset:54272
	ds_read_b128 v[224:227], v154 offset:55296
	ds_read_b128 v[228:231], v154 offset:56320
	global_load_lds_dwordx4 v[150:151], off
	s_add_i32 m0, s5, 0x2000
	s_add_u32 s10, s58, 0x40080
	v_lshl_add_u64 v[150:151], v[232:233], 0, s[36:37]
	s_addc_u32 s11, s59, 0
	s_add_i32 s5, s9, s63
	global_load_lds_dwordx4 v[150:151], off
	v_lshl_add_u64 v[150:151], s[10:11], 0, v[142:143]
	s_mov_b32 m0, s5
	s_nop 0
	global_load_lds_dwordx4 v[150:151], off
	v_lshl_add_u64 v[150:151], s[10:11], 0, v[138:139]
	s_add_i32 m0, s5, 0x2000
	s_nop 0
	global_load_lds_dwordx4 v[150:151], off
	v_lshl_add_u64 v[150:151], v[234:235], 0, s[36:37]
	s_mov_b32 m0, s70
	s_nop 0
	global_load_lds_dwordx4 v[150:151], off
	v_lshl_add_u64 v[150:151], v[236:237], 0, s[36:37]
	s_mov_b32 m0, s71
	s_nop 0
	global_load_lds_dwordx4 v[150:151], off
	s_waitcnt vmcnt(8)
	s_waitcnt lgkmcnt(0)
	s_barrier
	s_setprio 1
	s_waitcnt lgkmcnt(0)
	v_mfma_f32_16x16x32_bf16 v[60:63], v[156:159], v[200:203], v[60:63]
	v_mfma_f32_16x16x32_bf16 v[52:55], v[164:167], v[200:203], v[52:55]
	v_mfma_f32_16x16x32_bf16 v[44:47], v[156:159], v[208:211], v[44:47]
	v_mfma_f32_16x16x32_bf16 v[36:39], v[164:167], v[208:211], v[36:39]
	v_mfma_f32_16x16x32_bf16 v[28:31], v[156:159], v[216:219], v[28:31]
	v_mfma_f32_16x16x32_bf16 v[20:23], v[164:167], v[216:219], v[20:23]
	v_mfma_f32_16x16x32_bf16 v[12:15], v[156:159], v[224:227], v[12:15]
	v_mfma_f32_16x16x32_bf16 v[4:7], v[164:167], v[224:227], v[4:7]
	v_mfma_f32_16x16x32_bf16 v[60:63], v[160:163], v[204:207], v[60:63]
	v_mfma_f32_16x16x32_bf16 v[52:55], v[180:183], v[204:207], v[52:55]
	v_mfma_f32_16x16x32_bf16 v[44:47], v[160:163], v[212:215], v[44:47]
	v_mfma_f32_16x16x32_bf16 v[36:39], v[180:183], v[212:215], v[36:39]
	v_mfma_f32_16x16x32_bf16 v[28:31], v[160:163], v[220:223], v[28:31]
	v_mfma_f32_16x16x32_bf16 v[20:23], v[180:183], v[220:223], v[20:23]
	v_mfma_f32_16x16x32_bf16 v[12:15], v[160:163], v[228:231], v[12:15]
	v_mfma_f32_16x16x32_bf16 v[4:7], v[180:183], v[228:231], v[4:7]
	s_setprio 0
	s_setprio 1
	v_mfma_f32_16x16x32_bf16 v[56:59], v[184:187], v[200:203], v[56:59]
	v_mfma_f32_16x16x32_bf16 v[48:51], v[192:195], v[200:203], v[48:51]
	v_mfma_f32_16x16x32_bf16 v[40:43], v[184:187], v[208:211], v[40:43]
	v_mfma_f32_16x16x32_bf16 v[32:35], v[192:195], v[208:211], v[32:35]
	v_mfma_f32_16x16x32_bf16 v[24:27], v[184:187], v[216:219], v[24:27]
	v_mfma_f32_16x16x32_bf16 v[16:19], v[192:195], v[216:219], v[16:19]
	v_mfma_f32_16x16x32_bf16 v[8:11], v[184:187], v[224:227], v[8:11]
	v_mfma_f32_16x16x32_bf16 v[0:3], v[192:195], v[224:227], v[0:3]
	v_mfma_f32_16x16x32_bf16 v[56:59], v[188:191], v[204:207], v[56:59]
	v_mfma_f32_16x16x32_bf16 v[48:51], v[196:199], v[204:207], v[48:51]
	v_mfma_f32_16x16x32_bf16 v[40:43], v[188:191], v[212:215], v[40:43]
	v_mfma_f32_16x16x32_bf16 v[32:35], v[196:199], v[212:215], v[32:35]
	v_mfma_f32_16x16x32_bf16 v[24:27], v[188:191], v[220:223], v[24:27]
	v_mfma_f32_16x16x32_bf16 v[16:19], v[196:199], v[220:223], v[16:19]
	v_mfma_f32_16x16x32_bf16 v[8:11], v[188:191], v[228:231], v[8:11]
	v_mfma_f32_16x16x32_bf16 v[0:3], v[196:199], v[228:231], v[0:3]
	s_setprio 0
	s_barrier
	s_add_i32 s4, s4, 2
	s_add_u32 s56, s56, 0x100
	s_addc_u32 s57, s57, 0
	s_add_u32 s1, s1, 0x100
	s_addc_u32 s2, s2, 0
	s_cmp_gt_u32 s4, 13
	s_cbranch_scc0 .LBB0_963
	s_andn2_b64 vcc, s[46:47], s[38:39]
	s_and_b64 vcc, exec, vcc
	s_cbranch_vccz .LBB0_966
	s_barrier
.LBB0_966:
	v_pk_mul_f32 v[156:157], v[124:125], s[18:19] op_sel_hi:[1,0]
	v_pk_mul_f32 v[158:159], v[116:117], s[18:19] op_sel_hi:[1,0]
	v_pk_mul_f32 v[120:121], v[120:121], v[124:125]
	v_pk_mul_f32 v[114:115], v[114:115], v[118:119]
	v_pk_mul_f32 v[124:125], v[126:127], s[18:19] op_sel_hi:[1,0]
	v_pk_mul_f32 v[118:119], v[118:119], s[18:19] op_sel_hi:[1,0]
	v_exp_f32_e32 v156, v156
	v_exp_f32_e32 v157, v157
	v_exp_f32_e32 v158, v158
	v_exp_f32_e32 v159, v159
	v_exp_f32_e32 v124, v124
	v_exp_f32_e32 v125, v125
	v_exp_f32_e32 v118, v118
	v_exp_f32_e32 v119, v119
	v_pk_add_f32 v[156:157], v[156:157], 1.0 op_sel_hi:[1,0]
	v_pk_add_f32 v[158:159], v[158:159], 1.0 op_sel_hi:[1,0]
	v_pk_add_f32 v[124:125], v[124:125], 1.0 op_sel_hi:[1,0]
	v_pk_add_f32 v[118:119], v[118:119], 1.0 op_sel_hi:[1,0]
	v_lshl_add_u32 v155, s8, 8, v152
	v_mov_b64_e32 v[150:151], s[14:15]
	s_movk_i32 s1, 0x1600
	s_lshl_b32 s0, s0, 7
	v_rcp_f32_e32 v156, v156
	v_rcp_f32_e32 v157, v157
	v_pk_mul_f32 v[122:123], v[122:123], v[126:127]
	v_rcp_f32_e32 v126, v158
	v_rcp_f32_e32 v127, v159
	v_rcp_f32_e32 v124, v124
	v_rcp_f32_e32 v125, v125
	v_rcp_f32_e32 v118, v118
	v_rcp_f32_e32 v119, v119
	v_mad_i64_i32 v[150:151], s[4:5], v155, s1, v[150:151]
	s_ashr_i32 s1, s0, 31
	v_lshl_add_u64 v[150:151], s[0:1], 1, v[150:151]
	v_lshl_add_u64 v[150:151], v[150:151], 0, s[16:17]
	v_pk_mul_f32 v[112:113], v[112:113], v[116:117]
	v_lshl_add_u64 v[150:151], v[150:151], 0, v[128:129]
	v_pk_mul_f32 v[120:121], v[120:121], v[156:157]
	v_pk_mul_f32 v[116:117], v[112:113], v[126:127]
	v_pk_mul_f32 v[122:123], v[122:123], v[124:125]
	v_pk_mul_f32 v[118:119], v[114:115], v[118:119]
	v_cvt_pk_bf16_f32 v112, v120, v121
	v_cvt_pk_bf16_f32 v113, v122, v123
	v_cvt_pk_bf16_f32 v114, v116, v117
	v_pk_mul_f32 v[104:105], v[104:105], v[108:109]
	v_cvt_pk_bf16_f32 v115, v118, v119
	global_store_dwordx4 v[150:151], v[112:115], off
; #define GAS __attribute__((address_space(1)))
; __device__ __forceinline__ unsigned cvt_pk_bf16(float lo, float hi) { unsigned r; asm volatile("v_cvt_pk_bf16_f32 %0, %1, %2" : "=v"(r) : "v"(lo), "v"(hi)); return r; }
;     __device__ __forceinline__ void operator()(const f32x4 (&acc)[2][2][4][2], const Unit& u, int wr, int wc, int fr, int fq) const {
;     ...
;             for (int m = 0; m < 4; ++m) { GAS bf16_t* rowp = p0 + (size_t)(ai * HALF + m * 16) * DFF;
;                 const f32x4 g0 = acc[ai][0][m][0], g1 = acc[ai][0][m][1], u0 = acc[ai][1][m][0], u1 = acc[ai][1][m][1]; f32x4 v0, v1;
; #pragma unroll
;                 for (int hj = 0; hj < 2; ++hj) {
;                     const f32x2 ga = (f32x2){g0[2 * hj], g0[2 * hj + 1]}, gb = (f32x2){g1[2 * hj], g1[2 * hj + 1]}, ua = (f32x2){u0[2 * hj], u0[2 * hj + 1]}, ub = (f32x2){u1[2 * hj], u1[2 * hj + 1]};
;                     const f32x2 ta = ga * (-1.4426950408889634f), tb = gb * (-1.4426950408889634f);
;                     const f32x2 da = (f32x2){__builtin_amdgcn_exp2f(ta.x), __builtin_amdgcn_exp2f(ta.y)} + 1.0f, db = (f32x2){__builtin_amdgcn_exp2f(tb.x), __builtin_amdgcn_exp2f(tb.y)} + 1.0f;
;                     const f32x2 ra = (ga * ua) * (f32x2){__builtin_amdgcn_rcpf(da.x), __builtin_amdgcn_rcpf(da.y)}, rb = (gb * ub) * (f32x2){__builtin_amdgcn_rcpf(db.x), __builtin_amdgcn_rcpf(db.y)};
;                     v0[2 * hj] = ra.x; v0[2 * hj + 1] = ra.y; v1[2 * hj] = rb.x; v1[2 * hj + 1] = rb.y; }
;                 u32x4 w; w.x = cvt_pk_bf16(v0[0], v0[1]); w.y = cvt_pk_bf16(v0[2], v0[3]); w.z = cvt_pk_bf16(v1[0], v1[1]); w.w = cvt_pk_bf16(v1[2], v1[3]);
;                 *(GAS u32x4*)rowp = w; }
	v_pk_mul_f32 v[98:99], v[98:99], v[102:103]
	v_pk_mul_f32 v[102:103], v[102:103], s[18:19] op_sel_hi:[1,0]
	v_pk_mul_f32 v[114:115], v[100:101], s[18:19] op_sel_hi:[1,0]
	v_pk_mul_f32 v[112:113], v[108:109], s[18:19] op_sel_hi:[1,0]
	v_exp_f32_e32 v114, v114
	v_exp_f32_e32 v115, v115
	v_pk_mul_f32 v[108:109], v[110:111], s[18:19] op_sel_hi:[1,0]
	v_exp_f32_e32 v112, v112
	v_exp_f32_e32 v113, v113
	v_exp_f32_e32 v108, v108
	v_exp_f32_e32 v109, v109
	v_exp_f32_e32 v102, v102
	v_exp_f32_e32 v103, v103
	v_pk_add_f32 v[114:115], v[114:115], 1.0 op_sel_hi:[1,0]
	v_pk_add_f32 v[112:113], v[112:113], 1.0 op_sel_hi:[1,0]
	v_pk_mul_f32 v[106:107], v[106:107], v[110:111]
	v_rcp_f32_e32 v110, v114
	v_rcp_f32_e32 v111, v115
	v_pk_add_f32 v[108:109], v[108:109], 1.0 op_sel_hi:[1,0]
	v_pk_add_f32 v[102:103], v[102:103], 1.0 op_sel_hi:[1,0]
	v_rcp_f32_e32 v112, v112
	v_rcp_f32_e32 v113, v113
	v_rcp_f32_e32 v108, v108
	v_rcp_f32_e32 v109, v109
	v_rcp_f32_e32 v102, v102
	v_rcp_f32_e32 v103, v103
	v_pk_mul_f32 v[96:97], v[96:97], v[100:101]
	v_pk_mul_f32 v[104:105], v[104:105], v[112:113]
	v_pk_mul_f32 v[100:101], v[96:97], v[110:111]
	v_pk_mul_f32 v[106:107], v[106:107], v[108:109]
	v_pk_mul_f32 v[102:103], v[98:99], v[102:103]
	v_cvt_pk_bf16_f32 v96, v104, v105
	v_cvt_pk_bf16_f32 v97, v106, v107
	v_cvt_pk_bf16_f32 v98, v100, v101
	v_add_co_u32_e32 v100, vcc, s44, v150
	v_cvt_pk_bf16_f32 v99, v102, v103
	v_pk_mul_f32 v[88:89], v[88:89], v[92:93]
	s_nop 0
	v_addc_co_u32_e32 v101, vcc, 0, v151, vcc
	global_store_dwordx4 v[100:101], v[96:99], off
	v_pk_mul_f32 v[82:83], v[82:83], v[86:87]
	v_pk_mul_f32 v[86:87], v[86:87], s[18:19] op_sel_hi:[1,0]
	v_pk_mul_f32 v[98:99], v[84:85], s[18:19] op_sel_hi:[1,0]
	v_pk_mul_f32 v[96:97], v[92:93], s[18:19] op_sel_hi:[1,0]
	v_exp_f32_e32 v98, v98
	v_exp_f32_e32 v99, v99
	v_pk_mul_f32 v[92:93], v[94:95], s[18:19] op_sel_hi:[1,0]
	v_exp_f32_e32 v96, v96
	v_exp_f32_e32 v97, v97
	v_exp_f32_e32 v92, v92
	v_exp_f32_e32 v93, v93
	v_exp_f32_e32 v86, v86
	v_exp_f32_e32 v87, v87
	v_pk_add_f32 v[98:99], v[98:99], 1.0 op_sel_hi:[1,0]
	v_pk_add_f32 v[96:97], v[96:97], 1.0 op_sel_hi:[1,0]
	v_pk_mul_f32 v[90:91], v[90:91], v[94:95]
	v_rcp_f32_e32 v94, v98
	v_rcp_f32_e32 v95, v99
	v_pk_add_f32 v[92:93], v[92:93], 1.0 op_sel_hi:[1,0]
	v_pk_add_f32 v[86:87], v[86:87], 1.0 op_sel_hi:[1,0]
	v_rcp_f32_e32 v96, v96
	v_rcp_f32_e32 v97, v97
	v_rcp_f32_e32 v92, v92
	v_rcp_f32_e32 v93, v93
	v_rcp_f32_e32 v86, v86
	v_rcp_f32_e32 v87, v87
	v_pk_mul_f32 v[80:81], v[80:81], v[84:85]
	v_pk_mul_f32 v[88:89], v[88:89], v[96:97]
	v_pk_mul_f32 v[84:85], v[80:81], v[94:95]
	v_pk_mul_f32 v[90:91], v[90:91], v[92:93]
	v_pk_mul_f32 v[86:87], v[82:83], v[86:87]
	v_cvt_pk_bf16_f32 v80, v88, v89
	v_cvt_pk_bf16_f32 v81, v90, v91
	v_cvt_pk_bf16_f32 v82, v84, v85
	v_add_co_u32_e32 v84, vcc, s45, v150
	v_cvt_pk_bf16_f32 v83, v86, v87
	v_pk_mul_f32 v[72:73], v[72:73], v[76:77]
	s_nop 0
	v_addc_co_u32_e32 v85, vcc, 0, v151, vcc
	global_store_dwordx4 v[84:85], v[80:83], off
	v_pk_mul_f32 v[66:67], v[66:67], v[70:71]
	v_pk_mul_f32 v[70:71], v[70:71], s[18:19] op_sel_hi:[1,0]
	v_pk_mul_f32 v[82:83], v[68:69], s[18:19] op_sel_hi:[1,0]
	v_pk_mul_f32 v[80:81], v[76:77], s[18:19] op_sel_hi:[1,0]
	v_exp_f32_e32 v82, v82
	v_exp_f32_e32 v83, v83
	v_pk_mul_f32 v[76:77], v[78:79], s[18:19] op_sel_hi:[1,0]
	v_exp_f32_e32 v80, v80
	v_exp_f32_e32 v81, v81
	v_exp_f32_e32 v76, v76
	v_exp_f32_e32 v77, v77
	v_exp_f32_e32 v70, v70
	v_exp_f32_e32 v71, v71
	v_pk_add_f32 v[82:83], v[82:83], 1.0 op_sel_hi:[1,0]
	v_pk_add_f32 v[80:81], v[80:81], 1.0 op_sel_hi:[1,0]
	v_pk_mul_f32 v[74:75], v[74:75], v[78:79]
	v_rcp_f32_e32 v78, v82
	v_rcp_f32_e32 v79, v83
	v_pk_add_f32 v[76:77], v[76:77], 1.0 op_sel_hi:[1,0]
	v_pk_add_f32 v[70:71], v[70:71], 1.0 op_sel_hi:[1,0]
	v_rcp_f32_e32 v80, v80
	v_rcp_f32_e32 v81, v81
	v_rcp_f32_e32 v76, v76
	v_rcp_f32_e32 v77, v77
	v_rcp_f32_e32 v70, v70
	v_rcp_f32_e32 v71, v71
	v_pk_mul_f32 v[64:65], v[64:65], v[68:69]
	v_pk_mul_f32 v[72:73], v[72:73], v[80:81]
	v_pk_mul_f32 v[68:69], v[64:65], v[78:79]
	v_pk_mul_f32 v[74:75], v[74:75], v[76:77]
	v_pk_mul_f32 v[70:71], v[66:67], v[70:71]
	v_cvt_pk_bf16_f32 v64, v72, v73
	v_cvt_pk_bf16_f32 v65, v74, v75
	v_cvt_pk_bf16_f32 v66, v68, v69
	v_add_co_u32_e32 v68, vcc, s74, v150
	v_cvt_pk_bf16_f32 v67, v70, v71
	v_pk_mul_f32 v[56:57], v[56:57], v[60:61]
	s_nop 0
	v_addc_co_u32_e32 v69, vcc, 0, v151, vcc
	global_store_dwordx4 v[68:69], v[64:67], off
	v_pk_mul_f32 v[50:51], v[50:51], v[54:55]
	v_pk_mul_f32 v[54:55], v[54:55], s[18:19] op_sel_hi:[1,0]
	v_pk_mul_f32 v[66:67], v[52:53], s[18:19] op_sel_hi:[1,0]
	v_pk_mul_f32 v[64:65], v[60:61], s[18:19] op_sel_hi:[1,0]
	v_exp_f32_e32 v66, v66
	v_exp_f32_e32 v67, v67
	v_pk_mul_f32 v[60:61], v[62:63], s[18:19] op_sel_hi:[1,0]
	v_exp_f32_e32 v64, v64
	v_exp_f32_e32 v65, v65
	v_exp_f32_e32 v60, v60
	v_exp_f32_e32 v61, v61
	v_exp_f32_e32 v54, v54
	v_exp_f32_e32 v55, v55
	v_pk_add_f32 v[66:67], v[66:67], 1.0 op_sel_hi:[1,0]
	v_pk_add_f32 v[64:65], v[64:65], 1.0 op_sel_hi:[1,0]
	v_pk_mul_f32 v[58:59], v[58:59], v[62:63]
	v_rcp_f32_e32 v62, v66
	v_rcp_f32_e32 v63, v67
	v_pk_add_f32 v[60:61], v[60:61], 1.0 op_sel_hi:[1,0]
; #define GAS __attribute__((address_space(1)))
; __device__ __forceinline__ unsigned cvt_pk_bf16(float lo, float hi) { unsigned r; asm volatile("v_cvt_pk_bf16_f32 %0, %1, %2" : "=v"(r) : "v"(lo), "v"(hi)); return r; }
; #define PG8_BAR __builtin_amdgcn_s_barrier()
;     __device__ __forceinline__ void operator()(const f32x4 (&acc)[2][2][4][2], const Unit& u, int wr, int wc, int fr, int fq) const {
;     ...
;             for (int m = 0; m < 4; ++m) { GAS bf16_t* rowp = p0 + (size_t)(ai * HALF + m * 16) * DFF;
;                 const f32x4 g0 = acc[ai][0][m][0], g1 = acc[ai][0][m][1], u0 = acc[ai][1][m][0], u1 = acc[ai][1][m][1]; f32x4 v0, v1;
; #pragma unroll
;                 for (int hj = 0; hj < 2; ++hj) {
;                     const f32x2 ga = (f32x2){g0[2 * hj], g0[2 * hj + 1]}, gb = (f32x2){g1[2 * hj], g1[2 * hj + 1]}, ua = (f32x2){u0[2 * hj], u0[2 * hj + 1]}, ub = (f32x2){u1[2 * hj], u1[2 * hj + 1]};
;                     const f32x2 ta = ga * (-1.4426950408889634f), tb = gb * (-1.4426950408889634f);
;                     const f32x2 da = (f32x2){__builtin_amdgcn_exp2f(ta.x), __builtin_amdgcn_exp2f(ta.y)} + 1.0f, db = (f32x2){__builtin_amdgcn_exp2f(tb.x), __builtin_amdgcn_exp2f(tb.y)} + 1.0f;
;                     const f32x2 ra = (ga * ua) * (f32x2){__builtin_amdgcn_rcpf(da.x), __builtin_amdgcn_rcpf(da.y)}, rb = (gb * ub) * (f32x2){__builtin_amdgcn_rcpf(db.x), __builtin_amdgcn_rcpf(db.y)};
;                     v0[2 * hj] = ra.x; v0[2 * hj + 1] = ra.y; v1[2 * hj] = rb.x; v1[2 * hj + 1] = rb.y; }
;                 u32x4 w; w.x = cvt_pk_bf16(v0[0], v0[1]); w.y = cvt_pk_bf16(v0[2], v0[3]); w.z = cvt_pk_bf16(v1[0], v1[1]); w.w = cvt_pk_bf16(v1[2], v1[3]);
;                 *(GAS u32x4*)rowp = w; }
; template <class Epi, class Sched>
; __device__ __forceinline__ void gemm_phase(LAS unsigned char* lds, const int K, const Sched& S, const Epi& E) {
;     ...
;         if (wr == 0) PG8_BAR;
;         E(acc, cur, wr, wc, fr, fq);
;         if (!has_next) break;
; #pragma unroll
;         for (int a = 0; a < 2; ++a)
; #pragma unroll
;             for (int b = 0; b < 2; ++b)
; #pragma unroll
;                 for (int m = 0; m < 4; ++m)
; #pragma unroll
;                     for (int n = 0; n < 2; ++n) acc[a][b][m][n] = (f32x4){0.f, 0.f, 0.f, 0.f};
;         cur = nxt; cA = nA; cB = nB; ++ui;
;         if (wr == 1) PG8_BAR;
	v_pk_add_f32 v[54:55], v[54:55], 1.0 op_sel_hi:[1,0]
	v_rcp_f32_e32 v64, v64
	v_rcp_f32_e32 v65, v65
	v_rcp_f32_e32 v60, v60
	v_rcp_f32_e32 v61, v61
	v_rcp_f32_e32 v54, v54
	v_rcp_f32_e32 v55, v55
	v_pk_mul_f32 v[48:49], v[48:49], v[52:53]
	v_pk_mul_f32 v[56:57], v[56:57], v[64:65]
	v_pk_mul_f32 v[52:53], v[48:49], v[62:63]
	v_pk_mul_f32 v[58:59], v[58:59], v[60:61]
	v_pk_mul_f32 v[54:55], v[50:51], v[54:55]
	v_cvt_pk_bf16_f32 v48, v56, v57
	v_cvt_pk_bf16_f32 v49, v58, v59
	v_cvt_pk_bf16_f32 v50, v52, v53
	v_add_co_u32_e32 v52, vcc, s73, v150
	v_cvt_pk_bf16_f32 v51, v54, v55
	v_pk_mul_f32 v[40:41], v[40:41], v[44:45]
	s_nop 0
	v_addc_co_u32_e32 v53, vcc, 0, v151, vcc
	global_store_dwordx4 v[52:53], v[48:51], off
	v_pk_mul_f32 v[34:35], v[34:35], v[38:39]
	v_pk_mul_f32 v[38:39], v[38:39], s[18:19] op_sel_hi:[1,0]
	v_pk_mul_f32 v[50:51], v[36:37], s[18:19] op_sel_hi:[1,0]
	v_pk_mul_f32 v[48:49], v[44:45], s[18:19] op_sel_hi:[1,0]
	v_exp_f32_e32 v50, v50
	v_exp_f32_e32 v51, v51
	v_pk_mul_f32 v[44:45], v[46:47], s[18:19] op_sel_hi:[1,0]
	v_exp_f32_e32 v48, v48
	v_exp_f32_e32 v49, v49
	v_exp_f32_e32 v44, v44
	v_exp_f32_e32 v45, v45
	v_exp_f32_e32 v38, v38
	v_exp_f32_e32 v39, v39
	v_pk_add_f32 v[50:51], v[50:51], 1.0 op_sel_hi:[1,0]
	v_pk_add_f32 v[48:49], v[48:49], 1.0 op_sel_hi:[1,0]
	v_pk_mul_f32 v[42:43], v[42:43], v[46:47]
	v_rcp_f32_e32 v46, v50
	v_rcp_f32_e32 v47, v51
	v_pk_add_f32 v[44:45], v[44:45], 1.0 op_sel_hi:[1,0]
	v_pk_add_f32 v[38:39], v[38:39], 1.0 op_sel_hi:[1,0]
	v_rcp_f32_e32 v48, v48
	v_rcp_f32_e32 v49, v49
	v_rcp_f32_e32 v44, v44
	v_rcp_f32_e32 v45, v45
	v_rcp_f32_e32 v38, v38
	v_rcp_f32_e32 v39, v39
	v_pk_mul_f32 v[32:33], v[32:33], v[36:37]
	v_pk_mul_f32 v[40:41], v[40:41], v[48:49]
	v_pk_mul_f32 v[36:37], v[32:33], v[46:47]
	v_pk_mul_f32 v[42:43], v[42:43], v[44:45]
	v_pk_mul_f32 v[38:39], v[34:35], v[38:39]
	v_cvt_pk_bf16_f32 v32, v40, v41
	v_cvt_pk_bf16_f32 v33, v42, v43
	v_cvt_pk_bf16_f32 v34, v36, v37
	v_add_co_u32_e32 v36, vcc, s75, v150
	v_cvt_pk_bf16_f32 v35, v38, v39
	v_pk_mul_f32 v[24:25], v[24:25], v[28:29]
	s_nop 0
	v_addc_co_u32_e32 v37, vcc, 0, v151, vcc
	global_store_dwordx4 v[36:37], v[32:35], off
	v_pk_mul_f32 v[18:19], v[18:19], v[22:23]
	v_pk_mul_f32 v[22:23], v[22:23], s[18:19] op_sel_hi:[1,0]
	v_pk_mul_f32 v[34:35], v[20:21], s[18:19] op_sel_hi:[1,0]
	v_pk_mul_f32 v[32:33], v[28:29], s[18:19] op_sel_hi:[1,0]
	v_exp_f32_e32 v34, v34
	v_exp_f32_e32 v35, v35
	v_pk_mul_f32 v[28:29], v[30:31], s[18:19] op_sel_hi:[1,0]
	v_exp_f32_e32 v32, v32
	v_exp_f32_e32 v33, v33
	v_exp_f32_e32 v28, v28
	v_exp_f32_e32 v29, v29
	v_exp_f32_e32 v22, v22
	v_exp_f32_e32 v23, v23
	v_pk_add_f32 v[34:35], v[34:35], 1.0 op_sel_hi:[1,0]
	v_pk_add_f32 v[32:33], v[32:33], 1.0 op_sel_hi:[1,0]
	v_pk_mul_f32 v[26:27], v[26:27], v[30:31]
	v_rcp_f32_e32 v30, v34
	v_rcp_f32_e32 v31, v35
	v_pk_add_f32 v[28:29], v[28:29], 1.0 op_sel_hi:[1,0]
	v_pk_add_f32 v[22:23], v[22:23], 1.0 op_sel_hi:[1,0]
	v_rcp_f32_e32 v32, v32
	v_rcp_f32_e32 v33, v33
	v_rcp_f32_e32 v28, v28
	v_rcp_f32_e32 v29, v29
	v_rcp_f32_e32 v22, v22
	v_rcp_f32_e32 v23, v23
	v_pk_mul_f32 v[16:17], v[16:17], v[20:21]
	v_pk_mul_f32 v[24:25], v[24:25], v[32:33]
	v_pk_mul_f32 v[20:21], v[16:17], v[30:31]
	v_pk_mul_f32 v[26:27], v[26:27], v[28:29]
	v_pk_mul_f32 v[22:23], v[18:19], v[22:23]
	v_cvt_pk_bf16_f32 v16, v24, v25
	v_cvt_pk_bf16_f32 v17, v26, v27
	v_cvt_pk_bf16_f32 v18, v20, v21
	v_add_co_u32_e32 v20, vcc, s76, v150
	v_cvt_pk_bf16_f32 v19, v22, v23
	v_pk_mul_f32 v[8:9], v[8:9], v[12:13]
	s_nop 0
	v_addc_co_u32_e32 v21, vcc, 0, v151, vcc
	global_store_dwordx4 v[20:21], v[16:19], off
	v_pk_mul_f32 v[2:3], v[2:3], v[6:7]
	v_pk_mul_f32 v[6:7], v[6:7], s[18:19] op_sel_hi:[1,0]
	v_pk_mul_f32 v[18:19], v[4:5], s[18:19] op_sel_hi:[1,0]
	v_pk_mul_f32 v[16:17], v[12:13], s[18:19] op_sel_hi:[1,0]
	v_exp_f32_e32 v18, v18
	v_exp_f32_e32 v19, v19
	v_pk_mul_f32 v[12:13], v[14:15], s[18:19] op_sel_hi:[1,0]
	v_exp_f32_e32 v16, v16
	v_exp_f32_e32 v17, v17
	v_exp_f32_e32 v12, v12
	v_exp_f32_e32 v13, v13
	v_exp_f32_e32 v6, v6
	v_exp_f32_e32 v7, v7
	v_pk_add_f32 v[18:19], v[18:19], 1.0 op_sel_hi:[1,0]
	v_pk_add_f32 v[16:17], v[16:17], 1.0 op_sel_hi:[1,0]
	v_pk_mul_f32 v[10:11], v[10:11], v[14:15]
	v_rcp_f32_e32 v14, v18
	v_rcp_f32_e32 v15, v19
	v_pk_add_f32 v[12:13], v[12:13], 1.0 op_sel_hi:[1,0]
	v_pk_add_f32 v[6:7], v[6:7], 1.0 op_sel_hi:[1,0]
	v_rcp_f32_e32 v16, v16
	v_rcp_f32_e32 v17, v17
	v_rcp_f32_e32 v12, v12
	v_rcp_f32_e32 v13, v13
	v_rcp_f32_e32 v6, v6
	v_rcp_f32_e32 v7, v7
	v_pk_mul_f32 v[0:1], v[0:1], v[4:5]
	v_pk_mul_f32 v[8:9], v[8:9], v[16:17]
	v_pk_mul_f32 v[4:5], v[0:1], v[14:15]
	v_pk_mul_f32 v[10:11], v[10:11], v[12:13]
	v_pk_mul_f32 v[6:7], v[2:3], v[6:7]
	v_cvt_pk_bf16_f32 v0, v8, v9
	v_cvt_pk_bf16_f32 v1, v10, v11
	v_cvt_pk_bf16_f32 v2, v4, v5
	v_add_co_u32_e32 v4, vcc, 0xf2000, v150
	s_mov_b64 s[8:9], -1
	s_nop 0
	v_addc_co_u32_e32 v5, vcc, 0, v151, vcc
	s_andn2_b64 vcc, exec, s[38:39]
	v_cvt_pk_bf16_f32 v3, v6, v7
	global_store_dwordx4 v[4:5], v[0:3], off
	s_cbranch_vccnz .LBB0_959
	s_andn2_b64 vcc, exec, s[42:43]
	s_cbranch_vccnz .LBB0_958
	s_branch .LBB0_958
